# v098 + one static s_setprio 1 for waves 4-7 at P10 entry (strategy: static priority raise for the younger half)
# baseline (speedup 1.0000x reference)
; __global__ void __launch_bounds__(NT, 2) mk_fwd(Args args) {
;     ...
;     if (IN(10)) {
;         const float* fg = args.in[28];
;         for (int tok = gw; tok < MTOK; tok += NGW) {
.LBB0_883:
	s_cmp_lt_i32 s94, 11
	s_cselect_b64 s[2:3], -1, 0
	s_and_b64 s[0:1], s[2:3], s[0:1]
	s_and_b64 s[0:1], s[0:1], s[86:87]
	s_andn2_b64 vcc, exec, s[0:1]
	s_cbranch_vccnz .LBB0_913
	s_cmp_gt_u32 s85, 3
	s_cbranch_scc0 .Lp10_noprio
	s_setprio 1
